# hoist L1 invalidate (buffer_inv) of each quiescent acquire ahead of its poll / next to the leader's L2 write-back
# speedup vs baseline: 1.0162x; 1.0162x over previous
.LBB0_187:
	s_lshl_b32 s4, s33, 8
	s_add_u32 s25, s2, s4
	s_addc_u32 s24, s3, 0
	v_mov_b32_e32 v1, s25
	v_add_co_u32_e32 v4, vcc, 0x1000, v1
	v_mov_b32_e32 v1, s24
	s_nop 0
	v_addc_co_u32_e32 v5, vcc, 0, v1, vcc
	v_mov_b32_e32 v1, 1
	flat_atomic_add v1, v[4:5], v1 offset:1024 sc0
	v_cvt_f32_u32_e32 v3, v2
	v_sub_u32_e32 v4, 0, v2
	v_rcp_iflag_f32_e32 v3, v3
	s_nop 0
	v_mul_f32_e32 v3, 0x4f7ffffe, v3
	v_cvt_u32_f32_e32 v3, v3
	v_mul_lo_u32 v4, v4, v3
	v_mul_hi_u32 v4, v3, v4
	v_add_u32_e32 v3, v3, v4
	s_waitcnt vmcnt(0) lgkmcnt(0)
	v_mul_hi_u32 v3, v1, v3
	v_mul_lo_u32 v5, v3, v2
	v_add_u32_e32 v4, 1, v1
	v_sub_u32_e32 v1, v1, v5
	v_add_u32_e32 v6, 1, v3
	v_cmp_ge_u32_e32 vcc, v1, v2
	v_sub_u32_e32 v5, v1, v2
	s_nop 0
	v_cndmask_b32_e32 v3, v3, v6, vcc
	v_cndmask_b32_e32 v1, v1, v5, vcc
	v_add_u32_e32 v5, 1, v3
	v_cmp_ge_u32_e32 vcc, v1, v2
	s_nop 1
	v_cndmask_b32_e32 v1, v3, v5, vcc
	v_mad_u64_u32 v[2:3], s[4:5], v2, v1, v[2:3]
	v_cmp_ne_u32_e32 vcc, v4, v2
	s_and_saveexec_b64 s[4:5], vcc
	s_xor_b64 s[4:5], exec, s[4:5]
	s_cbranch_execz .LBB0_200
	v_mov_b32_e32 v0, s25
	v_add_co_u32_e32 v2, vcc, 0x2000, v0
	v_mov_b32_e32 v0, s24
	s_nop 0
	v_addc_co_u32_e32 v3, vcc, 0, v0, vcc
	buffer_inv sc1
	flat_load_dword v0, v[2:3] offset:1024 sc1
	s_add_u32 s8, s25, 0x2400
	s_addc_u32 s9, s24, 0
	s_waitcnt vmcnt(0) lgkmcnt(0)
	v_cmp_eq_u32_e32 vcc, v0, v1
	s_and_saveexec_b64 s[6:7], vcc
	s_cbranch_execz .LBB0_199
	s_mov_b32 s26, 1
	s_mov_b64 s[10:11], 0
	s_branch .LBB0_191

.LBB0_199:
	s_or_b64 exec, exec, s[6:7]
	s_waitcnt vmcnt(0) lgkmcnt(0)
	s_waitcnt vmcnt(0)
.LBB0_200:
	s_andn2_saveexec_b64 s[4:5], s[4:5]
	s_cbranch_execz .LBB0_216
	v_mov_b32_e32 v1, s2
	v_add_co_u32_e32 v2, vcc, 0x3000, v1
	v_mov_b32_e32 v1, s3
	buffer_wbl2 sc1
	buffer_inv sc1
	s_waitcnt vmcnt(0)
	v_addc_co_u32_e32 v3, vcc, 0, v1, vcc
	v_mov_b32_e32 v1, 1
	flat_atomic_add v1, v[2:3], v1 offset:1024 sc0
	v_cvt_f32_u32_e32 v2, v0
	v_sub_u32_e32 v3, 0, v0
	s_add_u32 s4, s2, 0x3500
	s_addc_u32 s5, s3, 0
	v_rcp_iflag_f32_e32 v2, v2
	s_mov_b64 s[8:9], -1
	v_mul_f32_e32 v2, 0x4f7ffffe, v2
	v_cvt_u32_f32_e32 v2, v2
	v_mul_lo_u32 v3, v3, v2
	v_mul_hi_u32 v3, v2, v3
	v_add_u32_e32 v2, v2, v3
	s_waitcnt vmcnt(0) lgkmcnt(0)
	v_mul_hi_u32 v2, v1, v2
	v_mul_lo_u32 v4, v2, v0
	v_add_u32_e32 v3, 1, v1
	v_sub_u32_e32 v1, v1, v4
	v_add_u32_e32 v5, 1, v2
	v_cmp_ge_u32_e32 vcc, v1, v0
	v_sub_u32_e32 v4, v1, v0
	s_nop 0
	v_cndmask_b32_e32 v2, v2, v5, vcc
	v_cndmask_b32_e32 v1, v1, v4, vcc
	v_add_u32_e32 v4, 1, v2
	v_cmp_ge_u32_e32 vcc, v1, v0
	s_nop 1
	v_cndmask_b32_e32 v2, v2, v4, vcc
	v_mad_u64_u32 v[0:1], s[6:7], v0, v2, v[0:1]
	v_cmp_ne_u32_e32 vcc, v3, v0
	v_mov_b64_e32 v[0:1], s[4:5]
	s_and_saveexec_b64 s[6:7], vcc
	s_cbranch_execz .LBB0_213
	v_mov_b64_e32 v[0:1], s[4:5]
	flat_load_dword v0, v[0:1] sc1
	s_mov_b64 s[12:13], 0
	s_waitcnt vmcnt(0) lgkmcnt(0)
	v_cmp_eq_u32_e32 vcc, v0, v2
	s_and_saveexec_b64 s[10:11], vcc
	s_cbranch_execz .LBB0_212
	s_add_u32 s8, s2, 0x200
	s_addc_u32 s9, s3, 0
	s_mov_b32 s22, 1
	s_mov_b64 s[2:3], 0
	s_branch .LBB0_205

.LBB0_215:
	s_or_b64 exec, exec, s[2:3]
	v_mov_b32_e32 v0, s25
	v_add_co_u32_e32 v0, vcc, 0x2000, v0
	v_mov_b32_e32 v1, s24
	s_nop 0
	v_addc_co_u32_e32 v1, vcc, 0, v1, vcc
	v_mov_b32_e32 v2, 1
	s_waitcnt vmcnt(0) lgkmcnt(0)
	flat_atomic_add v[0:1], v2 offset:1024
	s_waitcnt vmcnt(0)
.LBB0_216:
	s_or_b64 exec, exec, s[0:1]
	s_cmpk_lt_i32 s72, 0x400
	s_cselect_b64 s[0:1], -1, 0
	v_writelane_b32 v253, s0, 2
	s_ashr_i32 s73, s72, 31
	s_ashr_i32 s76, s71, 31
	v_writelane_b32 v253, s1, 3
	s_lshr_b32 s0, s73, 29
	s_add_i32 s0, s72, s0
	s_ashr_i32 s1, s0, 3
	s_and_b32 s0, s0, -8
	s_sub_i32 s2, s72, s0
	s_lshl_b32 s3, s2, 7
	s_cmpk_lt_i32 s72, 0x100
	s_cselect_b64 s[4:5], -1, 0
	v_writelane_b32 v253, s4, 4
	s_lshl_b32 s0, s72, 2
	s_bfe_u32 s7, s72, 0x30003
	v_writelane_b32 v253, s5, 5
	s_and_b32 s4, s0, 28
	s_ashr_i32 s5, s72, 6
	s_add_i32 s8, s4, s5
	s_ashr_i32 s9, s8, 31
	s_lshl_b64 s[4:5], s[8:9], 18
	v_writelane_b32 v253, s4, 6
	s_and_b32 s0, s0, 24
	s_lshl_b32 s10, s8, 4
	v_writelane_b32 v253, s5, 7
	s_lshl_b32 s4, s7, 17
	v_writelane_b32 v253, s4, 8
	s_lshl_b32 s5, s8, 8
	v_writelane_b32 v253, s5, 9
	s_and_b32 s5, s5, 0x1f00
	s_or_b32 s0, s0, s7
	s_lshl_b32 s4, s7, 6
	v_writelane_b32 v253, s5, 10
	s_lshl_b32 s5, s7, 7
	s_lshl_b64 s[12:13], s[8:9], 19
	s_lshl_b32 s9, s7, 18
	s_ashr_i32 s11, s10, 31
	s_lshl_b32 s0, s0, 4
	s_cmp_lt_i32 s2, 0
	s_mulk_i32 s2, 0x81
	s_cselect_b32 s2, s2, s3
	s_add_i32 s1, s2, s1
	s_ashr_i32 s2, s1, 31
	s_lshr_b32 s2, s2, 24
	s_add_i32 s2, s1, s2
	s_ashr_i32 s3, s2, 8
	s_and_b32 s2, s2, 0xff00
	s_sub_i32 s1, s1, s2
	s_sext_i32_i16 s2, s1
	s_bfe_u32 s2, s2, 0x3001c
	v_writelane_b32 v253, s5, 11
	s_add_i32 s5, s1, s2
	s_sext_i32_i16 s6, s5
	s_and_b32 s5, s5, 0xfff8
	s_sub_i32 s1, s1, s5
	v_writelane_b32 v253, s10, 12
	s_lshl_b32 s3, s3, 3
	s_sext_i32_i16 s1, s1
	v_writelane_b32 v253, s11, 13
	s_add_i32 s10, s3, s1
	s_ashr_i32 s1, s6, 3
	s_lshr_b32 s2, s6, 3
	v_writelane_b32 v253, s1, 14
	s_mov_b32 s6, s10
	s_ashr_i32 s11, s10, 31
	v_writelane_b32 v253, s6, 15
	s_lshl_b64 s[10:11], s[10:11], 19
	s_bfe_i64 s[2:3], s[2:3], 0x100000
	v_writelane_b32 v253, s7, 16
	v_writelane_b32 v253, s10, 17
	s_lshl_b64 s[2:3], s[2:3], 19
	s_add_i32 s1, s8, 32
	v_writelane_b32 v253, s11, 18
	v_writelane_b32 v253, s2, 19
	s_mov_b32 s97, 0
	s_mov_b32 s77, 0x10000
	v_writelane_b32 v253, s3, 20
	s_mov_b32 s2, s8
	v_writelane_b32 v253, s2, 21
	v_mov_b32_e32 v137, 0
	s_movk_i32 s78, 0x4000
	v_writelane_b32 v253, s3, 22
	v_writelane_b32 v253, s1, 23
	v_writelane_b32 v253, s7, 24
	s_or_b32 s1, s7, 8
	v_writelane_b32 v253, s1, 25
	s_add_u32 s1, s12, 0xd140080
	v_writelane_b32 v253, s1, 26
	v_writelane_b32 v253, s12, 27
	s_addc_u32 s1, s13, 0
	s_mov_b32 s3, 0x20000
	v_writelane_b32 v253, s13, 28
	v_writelane_b32 v253, s1, 29
	v_writelane_b32 v253, s9, 30
	s_add_u32 s1, s9, 0x3100100
	v_writelane_b32 v253, s1, 31
	s_addc_u32 s1, 0, 0
	v_writelane_b32 v253, s1, 32
	s_add_i32 s1, 0, 0x20140
	v_writelane_b32 v253, s1, 33
	s_mov_b32 s2, 0x1000000
	v_writelane_b32 v253, s0, 34
	s_movk_i32 s79, 0x6000
	s_mov_b32 s91, 0x18000
	v_writelane_b32 v253, s1, 35
	v_writelane_b32 v253, s2, 36
	v_writelane_b32 v253, s3, 37
	s_lshl_b32 s1, s4, 1
	v_writelane_b32 v253, s1, 38
	s_lshl_b32 s0, s0, 2
	v_writelane_b32 v253, s0, 39
	s_add_i32 s0, 0, 0xc400
	v_writelane_b32 v253, s0, 40
	s_add_i32 s0, 0, 0x20160
	v_writelane_b32 v253, s0, 41
	s_add_i32 s0, 0, 0x20164
	v_writelane_b32 v253, s0, 42
	s_add_i32 s0, 0, 0x1ae00
	v_writelane_b32 v253, s0, 43
	s_mov_b64 s[0:1], -1
	v_writelane_b32 v253, s0, 44
	s_mov_b32 s80, 0x8000
	s_mov_b32 s82, 0xa000
	v_writelane_b32 v253, s1, 45
	v_writelane_b32 v253, s72, 46
	s_mov_b32 s81, 0xc000
	s_mov_b32 s54, 0xe000
	v_writelane_b32 v253, s73, 47
	v_writelane_b32 v253, s74, 48
	s_mov_b32 s92, 0x24000
	s_mov_b32 s93, 0x28000
	v_writelane_b32 v253, s75, 49
	v_writelane_b32 v253, s71, 50
	v_writelane_b32 v253, s73, 51
	s_mov_b32 s94, 0x40000
	s_mov_b32 s95, 0x60000
	s_movk_i32 s84, 0x1000
	s_movk_i32 s85, 0xff
	s_movk_i32 s55, 0x80
	v_mov_b32_e32 v176, 1
	v_mov_b32_e32 v190, 0x358637bd
	v_mov_b32_e32 v192, 0x260
	v_mov_b32_e32 v177, 0x200
	v_mov_b32_e32 v193, 0xa00
	v_mov_b32_e32 v252, 0xe00
	v_mov_b32_e32 v191, 0xf149f2ca
	s_movk_i32 s90, 0x7fff
	s_mov_b32 s33, 0x3e38aa3b
	s_mov_b64 s[88:89], 0x80
	s_mov_b32 s8, s97
	s_movk_i32 s46, 0x2000
	v_writelane_b32 v253, s76, 52
	s_waitcnt lgkmcnt(0)
	s_barrier
	s_branch .LBB0_220
.LBB0_217:
	s_waitcnt vmcnt(0)
.LBB0_218:
	s_or_b64 exec, exec, s[0:1]
	s_mov_b64 s[0:1], 0
	s_barrier

.LBB0_437:
	s_lshl_b32 s4, s38, 8
	s_add_u32 s25, s2, s4
	s_addc_u32 s24, s3, 0
	v_mov_b32_e32 v1, s25
	v_add_co_u32_e32 v4, vcc, 0x1000, v1
	v_mov_b32_e32 v1, s24
	s_nop 0
	v_addc_co_u32_e32 v5, vcc, 0, v1, vcc
	flat_atomic_add v3, v[4:5], v176 offset:1024 sc0
	v_cvt_f32_u32_e32 v1, v2
	v_sub_u32_e32 v4, 0, v2
	v_rcp_iflag_f32_e32 v1, v1
	s_nop 0
	v_mul_f32_e32 v1, 0x4f7ffffe, v1
	v_cvt_u32_f32_e32 v1, v1
	v_mul_lo_u32 v4, v4, v1
	v_mul_hi_u32 v4, v1, v4
	v_add_u32_e32 v1, v1, v4
	s_waitcnt vmcnt(0) lgkmcnt(0)
	v_mul_hi_u32 v1, v3, v1
	v_mul_lo_u32 v4, v1, v2
	v_sub_u32_e32 v4, v3, v4
	v_cmp_ge_u32_e32 vcc, v4, v2
	v_add_u32_e32 v5, 1, v1
	s_nop 0
	v_cndmask_b32_e32 v1, v1, v5, vcc
	v_sub_u32_e32 v5, v4, v2
	v_cndmask_b32_e32 v4, v4, v5, vcc
	v_cmp_ge_u32_e32 vcc, v4, v2
	v_add_u32_e32 v4, 1, v1
	s_nop 0
	v_cndmask_b32_e32 v1, v1, v4, vcc
	v_add_u32_e32 v4, 1, v3
	v_mad_u64_u32 v[2:3], s[4:5], v2, v1, v[2:3]
	v_cmp_ne_u32_e32 vcc, v4, v2
	s_and_saveexec_b64 s[4:5], vcc
	s_xor_b64 s[4:5], exec, s[4:5]
	s_cbranch_execz .LBB0_450
	v_mov_b32_e32 v0, s25
	v_add_co_u32_e32 v2, vcc, 0x2000, v0
	v_mov_b32_e32 v0, s24
	s_nop 0
	v_addc_co_u32_e32 v3, vcc, 0, v0, vcc
	buffer_inv sc1
	flat_load_dword v0, v[2:3] offset:1024 sc1
	s_add_u32 s8, s25, 0x2400
	s_addc_u32 s9, s24, 0
	s_waitcnt vmcnt(0) lgkmcnt(0)
	v_cmp_eq_u32_e32 vcc, v0, v1
	s_and_saveexec_b64 s[6:7], vcc
	s_cbranch_execz .LBB0_449
	s_mov_b32 s26, 1
	s_mov_b64 s[10:11], 0
	s_branch .LBB0_441

.LBB0_450:
	s_andn2_saveexec_b64 s[4:5], s[4:5]
	s_cbranch_execz .LBB0_466
	v_mov_b32_e32 v1, s2
	v_add_co_u32_e32 v2, vcc, 0x3000, v1
	v_mov_b32_e32 v1, s3
	buffer_wbl2 sc1
	buffer_inv sc1
	s_waitcnt vmcnt(0)
	v_addc_co_u32_e32 v3, vcc, 0, v1, vcc
	flat_atomic_add v1, v[2:3], v176 offset:1024 sc0
	v_cvt_f32_u32_e32 v2, v0
	v_sub_u32_e32 v3, 0, v0
	s_mov_b64 s[8:9], -1
	v_rcp_iflag_f32_e32 v2, v2
	s_nop 0
	v_mul_f32_e32 v2, 0x4f7ffffe, v2
	v_cvt_u32_f32_e32 v2, v2
	v_mul_lo_u32 v3, v3, v2
	v_mul_hi_u32 v3, v2, v3
	v_add_u32_e32 v2, v2, v3
	s_waitcnt vmcnt(0) lgkmcnt(0)
	v_mul_hi_u32 v2, v1, v2
	v_mul_lo_u32 v3, v2, v0
	v_sub_u32_e32 v3, v1, v3
	v_cmp_ge_u32_e32 vcc, v3, v0
	v_add_u32_e32 v4, 1, v2
	s_nop 0
	v_cndmask_b32_e32 v2, v2, v4, vcc
	v_sub_u32_e32 v4, v3, v0
	v_cndmask_b32_e32 v3, v3, v4, vcc
	v_cmp_ge_u32_e32 vcc, v3, v0
	v_add_u32_e32 v3, 1, v2
	s_nop 0
	v_cndmask_b32_e32 v2, v2, v3, vcc
	v_add_u32_e32 v3, 1, v1
	v_mad_u64_u32 v[0:1], s[4:5], v0, v2, v[0:1]
	s_add_u32 s4, s2, 0x3500
	s_addc_u32 s5, s3, 0
	v_cmp_ne_u32_e32 vcc, v3, v0
	v_mov_b64_e32 v[0:1], s[4:5]
	s_and_saveexec_b64 s[6:7], vcc
	s_cbranch_execz .LBB0_463
	v_mov_b64_e32 v[0:1], s[4:5]
	flat_load_dword v0, v[0:1] sc1
	s_mov_b64 s[12:13], 0
	s_waitcnt vmcnt(0) lgkmcnt(0)
	v_cmp_eq_u32_e32 vcc, v0, v2
	s_and_saveexec_b64 s[10:11], vcc
	s_cbranch_execz .LBB0_462
	s_add_u32 s8, s2, 0x200
	s_addc_u32 s9, s3, 0
	s_mov_b32 s22, 1
	s_mov_b64 s[2:3], 0
	s_branch .LBB0_455

.LBB0_465:
	s_or_b64 exec, exec, s[2:3]
	v_mov_b32_e32 v0, s25
	v_add_co_u32_e32 v0, vcc, 0x2000, v0
	v_mov_b32_e32 v1, s24
	s_nop 0
	v_addc_co_u32_e32 v1, vcc, 0, v1, vcc
	s_waitcnt vmcnt(0) lgkmcnt(0)
	flat_atomic_add v[0:1], v176 offset:1024
	s_waitcnt vmcnt(0)

.LBB0_901:
	s_or_b64 exec, exec, s[4:5]
	s_mov_b64 s[4:5], s[74:75]
	s_getreg_b32 s2, hwreg(HW_REG_HW_ID, 0, 6)
	s_lshl_b32 s2, s2, 2
	s_and_b32 s2, s2, 0xfc
	s_add_i32 s2, s2, 0
	s_add_i32 s2, s2, 0x20200
	v_mov_b32_e32 v0, s2
	ds_read_b32 v0, v0
	v_mbcnt_lo_u32_b32 v1, -1, 0
	v_mbcnt_hi_u32_b32 v1, -1, v1
	s_waitcnt lgkmcnt(0)
	v_readfirstlane_b32 s2, v0
	s_lshl_b32 s2, s2, 6
	v_sub_u32_e32 v0, 0, v1
	v_cmp_eq_u32_e32 vcc, s2, v0
	s_and_saveexec_b64 s[2:3], vcc
	s_cbranch_execz .LBB0_914
	s_load_dwordx2 s[4:5], s[4:5], 0xf8
	s_lshl_b64 s[8:9], s[0:1], 2
	v_mov_b32_e32 v0, 0xb000
	s_waitcnt lgkmcnt(0)
	s_add_u32 s4, s4, s8
	s_addc_u32 s5, s5, s9
	buffer_inv sc1
	global_load_dword v0, v0, s[4:5] offset:1024 sc1
	s_add_u32 s4, s4, 0xb400
	s_addc_u32 s5, s5, 0
	s_waitcnt vmcnt(0)
	v_cmp_lt_u32_e32 vcc, 7, v0
	s_cbranch_vccnz .LBB0_913
	s_mov_b32 s10, 0x3ffff8
	s_branch .LBB0_905

.LBB0_905:
	s_sleep 1
	global_load_dword v0, v137, s[4:5] sc1
	s_mov_b64 s[8:9], -1
	s_waitcnt vmcnt(0)
	v_cmp_lt_u32_e32 vcc, 7, v0
	s_cbranch_vccnz .LBB0_904
	s_sleep 1
	global_load_dword v0, v137, s[4:5] sc1
	s_waitcnt vmcnt(0)
	v_cmp_gt_u32_e32 vcc, 8, v0
	s_cbranch_vccz .LBB0_904
	s_sleep 1
	global_load_dword v0, v137, s[4:5] sc1
	s_waitcnt vmcnt(0)
	v_cmp_gt_u32_e32 vcc, 8, v0
	s_cbranch_vccz .LBB0_904
	s_sleep 1
	global_load_dword v0, v137, s[4:5] sc1
	s_waitcnt vmcnt(0)
	v_cmp_gt_u32_e32 vcc, 8, v0
	s_cbranch_vccz .LBB0_904
	s_sleep 1
	global_load_dword v0, v137, s[4:5] sc1
	s_waitcnt vmcnt(0)
	v_cmp_gt_u32_e32 vcc, 8, v0
	s_cbranch_vccz .LBB0_904
	s_sleep 1
	global_load_dword v0, v137, s[4:5] sc1
	s_waitcnt vmcnt(0)
	v_cmp_gt_u32_e32 vcc, 8, v0
	s_cbranch_vccz .LBB0_904
	s_sleep 1
	global_load_dword v0, v137, s[4:5] sc1
	s_cmp_eq_u32 s10, 0
	s_cselect_b64 s[8:9], -1, 0
	s_waitcnt vmcnt(0)
	v_cmp_lt_u32_e32 vcc, 7, v0
	s_or_b64 s[8:9], vcc, s[8:9]
	s_andn2_b64 vcc, exec, s[8:9]
	s_mov_b64 s[8:9], -1
	s_cbranch_vccz .LBB0_904
	s_sleep 1
	global_load_dword v0, v137, s[4:5] sc1
	s_add_i32 s10, s10, -8
	s_waitcnt vmcnt(0)
	v_cmp_lt_u32_e64 s[8:9], 7, v0
	s_branch .LBB0_904
.LBB0_913:
	s_waitcnt vmcnt(0)
.LBB0_914:
	s_or_b64 exec, exec, s[2:3]
	s_mov_b64 s[8:9], s[74:75]
	s_mov_b64 s[4:5], s[74:75]
	s_mov_b64 s[2:3], s[74:75]
	s_barrier
	s_getreg_b32 s10, hwreg(HW_REG_HW_ID, 0, 6)
	s_lshl_b32 s10, s10, 2
	s_and_b32 s10, s10, 0xfc
	s_add_i32 s10, s10, 0
	s_add_i32 s10, s10, 0x20200
	v_mov_b32_e32 v0, s10
	ds_read_b32 v0, v0
	v_mbcnt_lo_u32_b32 v32, -1, 0
	v_mbcnt_hi_u32_b32 v32, -1, v32
	s_and_b64 vcc, exec, s[6:7]
	s_waitcnt lgkmcnt(0)
	v_readfirstlane_b32 s10, v0
	s_nop 1
	v_lshl_add_u32 v0, s10, 6, v32
	s_nop 0
	v_readfirstlane_b32 s12, v0
	s_cbranch_vccnz .LBB0_946
	v_lshlrev_b32_e32 v1, 4, v0
	v_add_u32_e32 v2, 0x2000, v1
	v_ashrrev_i32_e32 v3, 31, v2
	v_lshrrev_b32_e32 v3, 22, v3
	v_add_u32_e32 v3, v2, v3
	s_load_dwordx2 s[8:9], s[8:9], 0xf8
	s_nop 0
	s_load_dwordx2 s[4:5], s[4:5], 0xf8
	s_nop 0
	s_load_dwordx2 s[14:15], s[2:3], 0xf8
	v_ashrrev_i32_e32 v3, 10, v3
	v_mul_i32_i24_e32 v4, 0x400, v3
	v_sub_u32_e32 v2, v2, v4
	s_waitcnt lgkmcnt(0)
	s_add_u32 s26, s8, 0x6900000
	v_lshrrev_b32_e32 v4, 4, v2
	s_addc_u32 s27, s9, 0
	s_lshl_b64 s[2:3], s[40:41], 22
	v_bitop3_b32 v2, v4, v2, 32 bitop3:0x6c
	s_add_u32 s2, s4, s2
	v_ashrrev_i32_e32 v4, 31, v2
	s_addc_u32 s3, s5, s3
	v_lshrrev_b32_e32 v4, 26, v4
	s_add_u32 s28, s2, 0x2900000
	v_add_u32_e32 v4, v2, v4
	v_lshlrev_b32_e32 v6, 3, v3
	s_addc_u32 s29, s3, 0
	s_ashr_i32 s2, s12, 6
	v_ashrrev_i32_e32 v5, 6, v4
	v_and_b32_e32 v6, -16, v6
	v_and_b32_e32 v4, 0xc0, v4
	s_lshl_b32 s30, s2, 10
	s_lshl_b32 s2, s2, 5
	v_add_u32_e32 v6, v5, v6
	v_sub_u32_e32 v2, v2, v4
	s_and_b32 s34, s2, 0x60
	v_and_b32_e32 v5, 3, v5
	s_mov_b32 s2, 0x3fffe0
	v_lshrrev_b32_e32 v7, 2, v6
	v_lshlrev_b32_e32 v8, 1, v6
	v_lshlrev_b32_e32 v3, 5, v3
	v_ashrrev_i16_sdwa v2, v176, sext(v2) dst_sel:DWORD dst_unused:UNUSED_PAD src0_sel:DWORD src1_sel:BYTE_0
	v_and_or_b32 v5, v6, s2, v5
	v_and_b32_e32 v7, 4, v7
	v_and_b32_e32 v8, 24, v8
	v_and_b32_e32 v3, 32, v3
	v_bfe_i32 v2, v2, 0, 16
	v_or3_b32 v5, v5, v7, v8
	v_add_lshl_u32 v2, v3, v2, 1
	v_lshl_add_u32 v96, v5, 10, v2
	v_lshl_add_u32 v98, v6, 10, v2
	v_bfe_i32 v2, v0, 27, 1
	v_lshrrev_b32_e32 v2, 22, v2
	v_add_u32_e32 v2, v1, v2
	v_and_b32_e32 v2, 0xfffffc00, v2
	v_sub_u32_e32 v1, v1, v2
	v_lshrrev_b32_e32 v2, 4, v1
	v_ashrrev_i32_e32 v4, 31, v0
	v_bitop3_b32 v1, v2, v1, 32 bitop3:0x6c
	v_lshrrev_b32_e32 v4, 26, v4
	v_ashrrev_i32_e32 v2, 31, v1
	v_add_u32_e32 v0, v0, v4
	v_lshrrev_b32_e32 v2, 26, v2
	v_ashrrev_i32_e32 v0, 6, v0
	v_add_u32_e32 v2, v1, v2
	v_lshlrev_b32_e32 v4, 3, v0
	v_ashrrev_i32_e32 v3, 6, v2
	v_and_b32_e32 v4, -16, v4
	s_ashr_i32 s13, s12, 8
	v_add_u32_e32 v4, v3, v4
	v_and_b32_e32 v3, 3, v3
	s_lshl_b32 s31, s13, 6
	v_and_or_b32 v3, v4, s2, v3
	v_readlane_b32 s2, v253, 8
	v_and_b32_e32 v2, 0xc0, v2
	s_add_u32 s8, s28, s2
	s_getreg_b32 s2, hwreg(HW_REG_HW_ID, 0, 6)
	v_sub_u32_e32 v1, v1, v2
	s_addc_u32 s9, s29, 0
	s_lshl_b32 s2, s2, 2
	v_lshrrev_b32_e32 v5, 2, v4
	v_lshlrev_b32_e32 v6, 1, v4
	v_lshlrev_b32_e32 v0, 5, v0
	v_ashrrev_i16_sdwa v1, v176, sext(v1) dst_sel:DWORD dst_unused:UNUSED_PAD src0_sel:DWORD src1_sel:BYTE_0
	s_and_b32 s2, s2, 0xfc
	v_and_b32_e32 v5, 4, v5
	v_and_b32_e32 v6, 24, v6
	v_and_b32_e32 v0, 32, v0
	v_bfe_i32 v1, v1, 0, 16
	s_add_i32 s2, s2, 0
	v_or3_b32 v3, v3, v5, v6
	v_add_lshl_u32 v0, v0, v1, 1
	s_add_i32 s2, s2, 0x20200
	v_lshl_add_u32 v100, v3, 10, v0
	v_lshl_add_u32 v102, v4, 10, v0
	v_mov_b32_e32 v0, s2
	ds_read_b32 v0, v0
	v_readlane_b32 s2, v253, 10
	s_waitcnt lgkmcnt(0)
	v_mbcnt_lo_u32_b32 v0, -1, 0
	v_mbcnt_hi_u32_b32 v0, -1, v0
	s_add_i32 s35, s31, s2
	v_and_or_b32 v8, v0, 15, s35
	v_lshrrev_b32_e32 v0, 1, v0
	v_readlane_b32 s2, v253, 11
	v_ashrrev_i32_e32 v9, 31, v8
	s_mov_b32 s4, 0x100000
	v_and_or_b32 v0, v0, 24, s2
	v_or_b32_e32 v0, s34, v0
	s_add_u32 s2, s14, 0x8900000
	s_addc_u32 s3, s15, 0
	v_lshlrev_b32_e32 v136, 1, v0
	v_lshl_add_u64 v[10:11], s[2:3], 0, v[136:137]
	v_lshlrev_b64 v[0:1], 13, v[8:9]
	v_lshl_add_u64 v[24:25], v[10:11], 0, v[0:1]
	v_add_co_u32_e32 v16, vcc, s4, v24
	s_mov_b32 s4, 0x120000
	s_nop 0
	v_addc_co_u32_e32 v17, vcc, 0, v25, vcc
	v_add_co_u32_e32 v20, vcc, s4, v24
	s_mov_b32 s4, 0x140000
	s_nop 0
	v_addc_co_u32_e32 v21, vcc, 0, v25, vcc
	v_or_b32_e32 v0, 16, v8
	v_or_b32_e32 v12, 32, v8
	v_or_b32_e32 v8, 48, v8
	v_add_co_u32_e32 v26, vcc, s4, v24
	v_ashrrev_i32_e32 v1, 31, v0
	v_ashrrev_i32_e32 v13, 31, v12
	v_ashrrev_i32_e32 v9, 31, v8
	v_addc_co_u32_e32 v27, vcc, 0, v25, vcc
	s_mov_b32 s4, 0x160000
	v_lshlrev_b64 v[0:1], 13, v[0:1]
	v_lshlrev_b64 v[12:13], 13, v[12:13]
	v_lshlrev_b64 v[8:9], 13, v[8:9]
	v_add_co_u32_e32 v28, vcc, s4, v24
	s_add_i32 s36, s30, 0
	v_lshl_add_u64 v[4:5], v[10:11], 0, v[0:1]
	v_lshl_add_u64 v[12:13], v[10:11], 0, v[12:13]
	v_lshl_add_u64 v[14:15], v[10:11], 0, v[8:9]
	v_addc_co_u32_e32 v29, vcc, 0, v25, vcc
	s_add_i32 m0, s36, 0x10000
	global_load_dwordx4 v[0:3], v[24:25], off
	s_nop 0
	global_load_dwordx4 v[4:7], v[4:5], off
	s_nop 0
	global_load_dwordx4 v[8:11], v[12:13], off
	s_nop 0
	global_load_dwordx4 v[12:15], v[14:15], off
	s_nop 0
	global_load_dwordx4 v[16:19], v[16:17], off
	s_nop 0
	global_load_dwordx4 v[20:23], v[20:21], off
	s_nop 0
	global_load_dwordx4 v[24:27], v[26:27], off
	s_nop 0
	global_load_dwordx4 v[28:31], v[28:29], off
	v_readlane_b32 s4, v253, 6
	global_load_lds_dwordx4 v100, s[8:9]
	s_add_i32 m0, s36, 0x12000
	v_readlane_b32 s5, v253, 7
	s_add_u32 s10, s26, s4
	s_addc_u32 s11, s27, s5
	s_add_i32 s37, s36, 0x2000
	global_load_lds_dwordx4 v96, s[8:9]
	s_mov_b32 m0, s36
	s_add_u32 s4, s10, 0x20000
	global_load_lds_dwordx4 v102, s[10:11]
	s_mov_b32 m0, s37
	s_addc_u32 s5, s11, 0
	s_add_i32 s38, s36, 0x4000
	global_load_lds_dwordx4 v98, s[10:11]
	s_mov_b32 m0, s38
	s_add_i32 s39, s36, 0x6000
	global_load_lds_dwordx4 v102, s[4:5]
	s_mov_b32 m0, s39
	s_cmp_eq_u32 s13, 1
	global_load_lds_dwordx4 v98, s[4:5]
	v_mov_b32_e32 v197, 0xa00
	s_cselect_b64 s[4:5], -1, 0
	s_cmp_lg_u32 s13, 1
	s_cbranch_scc1 .LBB0_917
	s_barrier

.LBB0_949:
	s_or_b64 exec, exec, s[4:5]
	s_mov_b64 s[4:5], s[74:75]
	s_getreg_b32 s2, hwreg(HW_REG_HW_ID, 0, 6)
	s_lshl_b32 s2, s2, 2
	s_and_b32 s2, s2, 0xfc
	s_add_i32 s2, s2, 0
	s_add_i32 s2, s2, 0x20200
	v_mov_b32_e32 v0, s2
	ds_read_b32 v0, v0
	v_mbcnt_lo_u32_b32 v1, -1, 0
	v_mbcnt_hi_u32_b32 v1, -1, v1
	s_waitcnt lgkmcnt(0)
	v_readfirstlane_b32 s2, v0
	s_lshl_b32 s2, s2, 6
	v_sub_u32_e32 v0, 0, v1
	v_cmp_eq_u32_e32 vcc, s2, v0
	s_and_saveexec_b64 s[2:3], vcc
	s_cbranch_execz .LBB0_962
	s_load_dwordx2 s[4:5], s[4:5], 0xf8
	s_lshl_b64 s[0:1], s[0:1], 2
	v_mov_b32_e32 v0, 0xc000
	s_waitcnt lgkmcnt(0)
	s_add_u32 s0, s4, s0
	s_addc_u32 s1, s5, s1
	buffer_inv sc1
	global_load_dword v0, v0, s[0:1] offset:2048 sc1
	s_add_u32 s0, s0, 0xc800
	s_addc_u32 s1, s1, 0
	s_waitcnt vmcnt(0)
	v_cmp_lt_u32_e32 vcc, 7, v0
	s_cbranch_vccnz .LBB0_961
	s_mov_b32 s8, 0x3ffff8
	s_branch .LBB0_953

.LBB0_953:
	s_sleep 1
	global_load_dword v0, v137, s[0:1] sc1
	s_mov_b64 s[4:5], -1
	s_waitcnt vmcnt(0)
	v_cmp_lt_u32_e32 vcc, 7, v0
	s_cbranch_vccnz .LBB0_952
	s_sleep 1
	global_load_dword v0, v137, s[0:1] sc1
	s_waitcnt vmcnt(0)
	v_cmp_gt_u32_e32 vcc, 8, v0
	s_cbranch_vccz .LBB0_952
	s_sleep 1
	global_load_dword v0, v137, s[0:1] sc1
	s_waitcnt vmcnt(0)
	v_cmp_gt_u32_e32 vcc, 8, v0
	s_cbranch_vccz .LBB0_952
	s_sleep 1
	global_load_dword v0, v137, s[0:1] sc1
	s_waitcnt vmcnt(0)
	v_cmp_gt_u32_e32 vcc, 8, v0
	s_cbranch_vccz .LBB0_952
	s_sleep 1
	global_load_dword v0, v137, s[0:1] sc1
	s_waitcnt vmcnt(0)
	v_cmp_gt_u32_e32 vcc, 8, v0
	s_cbranch_vccz .LBB0_952
	s_sleep 1
	global_load_dword v0, v137, s[0:1] sc1
	s_waitcnt vmcnt(0)
	v_cmp_gt_u32_e32 vcc, 8, v0
	s_cbranch_vccz .LBB0_952
	s_sleep 1
	global_load_dword v0, v137, s[0:1] sc1
	s_cmp_eq_u32 s8, 0
	s_cselect_b64 s[4:5], -1, 0
	s_waitcnt vmcnt(0)
	v_cmp_lt_u32_e32 vcc, 7, v0
	s_or_b64 s[4:5], vcc, s[4:5]
	s_andn2_b64 vcc, exec, s[4:5]
	s_mov_b64 s[4:5], -1
	s_cbranch_vccz .LBB0_952
	s_sleep 1
	global_load_dword v0, v137, s[0:1] sc1
	s_add_i32 s8, s8, -8
	s_waitcnt vmcnt(0)
	v_cmp_lt_u32_e64 s[4:5], 7, v0
	s_branch .LBB0_952
.LBB0_961:
	s_waitcnt vmcnt(0)
.LBB0_962:
	s_or_b64 exec, exec, s[2:3]
	s_mov_b64 s[2:3], s[74:75]
	s_mov_b64 s[8:9], s[74:75]
	s_mov_b64 s[0:1], s[74:75]
	s_mov_b64 s[12:13], s[74:75]
	s_barrier
	s_getreg_b32 s4, hwreg(HW_REG_HW_ID, 0, 6)
	s_lshl_b32 s4, s4, 2
	s_and_b32 s4, s4, 0xfc
	s_add_i32 s4, s4, 0
	s_add_i32 s4, s4, 0x20200
	v_mov_b32_e32 v0, s4
	ds_read_b32 v0, v0
	v_mbcnt_lo_u32_b32 v56, -1, 0
	v_mbcnt_hi_u32_b32 v56, -1, v56
	s_and_b64 vcc, exec, s[6:7]
	s_waitcnt lgkmcnt(0)
	v_readfirstlane_b32 s4, v0
	s_nop 1
	v_lshl_add_u32 v30, s4, 6, v56
	s_nop 0
	v_readfirstlane_b32 s17, v30
	s_cbranch_vccnz .LBB0_1074
	s_load_dwordx2 s[4:5], s[2:3], 0xf8
	s_nop 0
	s_load_dwordx2 s[2:3], s[8:9], 0xf8
	s_nop 0
	s_load_dwordx4 s[8:11], s[12:13], 0xf0
	s_getreg_b32 s6, hwreg(HW_REG_HW_ID, 0, 6)
	s_lshl_b32 s6, s6, 2
	s_and_b32 s6, s6, 0xfc
	s_add_i32 s6, s6, 0
	s_add_i32 s6, s6, 0x20200
	v_mov_b32_e32 v0, s6
	s_ashr_i32 s20, s17, 8
	ds_read_b32 v0, v0
	s_lshl_b32 s16, s20, 6
	v_readlane_b32 s12, v253, 61
	v_mbcnt_lo_u32_b32 v4, -1, 0
	v_mbcnt_hi_u32_b32 v4, -1, v4
	v_readlane_b32 s6, v253, 9
	s_waitcnt lgkmcnt(0)
	v_and_or_b32 v0, v4, 15, s16
	v_readlane_b32 s13, v253, 62
	v_add_u32_e32 v24, s6, v0
	s_mov_b64 s[6:7], -1
	s_and_b64 vcc, exec, s[12:13]
	s_cbranch_vccz .LBB0_965
	v_ashrrev_i32_e32 v25, 31, v24
	s_mov_b64 s[6:7], 0
	v_mov_b64_e32 v[0:1], v[24:25]

.LBB0_1079:
	s_load_dwordx2 s[2:3], s[2:3], 0xf8
	v_readlane_b32 s4, v253, 39
	v_mov_b32_e32 v0, 0xd000
	s_waitcnt lgkmcnt(0)
	s_add_u32 s2, s2, s4
	s_addc_u32 s3, s3, 0
	buffer_inv sc1
	global_load_dword v0, v0, s[2:3] offset:3072 sc1
	s_add_u32 s2, s2, 0xdc00
	s_addc_u32 s3, s3, 0
	s_waitcnt vmcnt(0)
	v_cmp_lt_u32_e32 vcc, 7, v0
	s_cbranch_vccz .LBB0_1080
	s_getpc_b64 s[98:99]
